# MLA part1 stage-2 pipelined step with the LDS-DMA issue of the next K/V tile moved from the step top to mid-step (after PV of previous tile), 2-pair address temps
# speedup vs baseline: 1.0083x; 1.0083x over previous
.LBB0_784:
	s_waitcnt vmcnt(0)
	s_add_i32 s5, s2, 1
	s_cmp_eq_u32 s2, 33
	s_waitcnt vmcnt(0) lgkmcnt(0)
	s_barrier
.LBB0_786:
	s_bitcmp1_b32 s2, 0
	s_cselect_b32 s2, 0xa000, 0
	v_add_u32_e32 v96, s2, v95
	ds_read_b128 v[172:175], v96
	ds_read_b128 v[176:179], v96 offset:1024
	ds_read_b128 v[188:191], v96 offset:2048
	ds_read_b128 v[192:195], v96 offset:3072
	ds_read_b128 v[198:201], v96 offset:4096
	ds_read_b128 v[202:205], v96 offset:5120
	s_cmp_eq_u32 s5, 1
	s_cbranch_scc1 .Lmy_first
	s_waitcnt lgkmcnt(5)
	v_mfma_f32_32x32x16_bf16 v[64:79], v[172:175], v[82:85], 0
	ds_read_b128 v[172:175], v96 offset:6144
	s_waitcnt lgkmcnt(5)
	v_mfma_f32_32x32x16_bf16 v[64:79], v[176:179], v[86:89], v[64:79]
	ds_read_b128 v[176:179], v96 offset:7168
	v_max_f32_e32 v111, v219, v219
	v_max_f32_e32 v159, v218, v218
	v_max_f32_e32 v111, v159, v111
	v_max3_f32 v111, v111, v220, v221
	v_max3_f32 v111, v111, v222, v223
	v_max3_f32 v111, v111, v224, v225
	v_max3_f32 v111, v111, v226, v227
	v_max3_f32 v111, v111, v228, v229
	v_max3_f32 v111, v111, v230, v231
	v_max3_f32 v111, v111, v232, v233
	v_mov_b32_e32 v159, v111
	s_nop 1
	v_permlane32_swap_b32_e32 v111, v159
	v_max_f32_e32 v159, v159, v159
	v_max_f32_e32 v111, v111, v111
	v_max_f32_e32 v111, v111, v159
	v_mul_f32_e32 v111, 0x3dd53b94, v111
	v_cmp_le_f32_e32 vcc, v111, v110
	s_cmp_eq_u64 vcc, exec
	s_cbranch_scc1 .LBB0_790
	v_max_f32_e32 v110, v111, v111
	v_max_f32_e32 v111, v80, v80
	v_max_f32_e32 v111, v111, v110
	v_sub_f32_e32 v80, v80, v111
	v_exp_f32_e32 v80, v80
	v_xor_b32_e32 v110, 0x80000000, v111
	v_mul_f32_e32 v81, v81, v80
	v_pk_mul_f32 v[62:63], v[62:63], v[80:81] op_sel_hi:[1,0]
	v_pk_mul_f32 v[60:61], v[60:61], v[80:81] op_sel_hi:[1,0]
	v_pk_mul_f32 v[58:59], v[58:59], v[80:81] op_sel_hi:[1,0]
	v_pk_mul_f32 v[56:57], v[56:57], v[80:81] op_sel_hi:[1,0]
	v_pk_mul_f32 v[54:55], v[54:55], v[80:81] op_sel_hi:[1,0]
	v_pk_mul_f32 v[52:53], v[52:53], v[80:81] op_sel_hi:[1,0]
	v_pk_mul_f32 v[50:51], v[50:51], v[80:81] op_sel_hi:[1,0]
	v_pk_mul_f32 v[48:49], v[48:49], v[80:81] op_sel_hi:[1,0]
	v_pk_mul_f32 v[46:47], v[46:47], v[80:81] op_sel_hi:[1,0]
	v_pk_mul_f32 v[44:45], v[44:45], v[80:81] op_sel_hi:[1,0]
	v_pk_mul_f32 v[42:43], v[42:43], v[80:81] op_sel_hi:[1,0]
	v_pk_mul_f32 v[40:41], v[40:41], v[80:81] op_sel_hi:[1,0]
	v_pk_mul_f32 v[38:39], v[38:39], v[80:81] op_sel_hi:[1,0]
	v_pk_mul_f32 v[36:37], v[36:37], v[80:81] op_sel_hi:[1,0]
	v_pk_mul_f32 v[34:35], v[34:35], v[80:81] op_sel_hi:[1,0]
	v_pk_mul_f32 v[32:33], v[32:33], v[80:81] op_sel_hi:[1,0]
	v_pk_mul_f32 v[30:31], v[30:31], v[80:81] op_sel_hi:[1,0]
	v_pk_mul_f32 v[28:29], v[28:29], v[80:81] op_sel_hi:[1,0]
	v_pk_mul_f32 v[26:27], v[26:27], v[80:81] op_sel_hi:[1,0]
	v_pk_mul_f32 v[24:25], v[24:25], v[80:81] op_sel_hi:[1,0]
	v_pk_mul_f32 v[22:23], v[22:23], v[80:81] op_sel_hi:[1,0]
	v_pk_mul_f32 v[20:21], v[20:21], v[80:81] op_sel_hi:[1,0]
	v_pk_mul_f32 v[18:19], v[18:19], v[80:81] op_sel_hi:[1,0]
	v_pk_mul_f32 v[16:17], v[16:17], v[80:81] op_sel_hi:[1,0]
	v_pk_mul_f32 v[14:15], v[14:15], v[80:81] op_sel_hi:[1,0]
	v_pk_mul_f32 v[12:13], v[12:13], v[80:81] op_sel_hi:[1,0]
	v_pk_mul_f32 v[10:11], v[10:11], v[80:81] op_sel_hi:[1,0]
	v_pk_mul_f32 v[8:9], v[8:9], v[80:81] op_sel_hi:[1,0]
	v_pk_mul_f32 v[6:7], v[6:7], v[80:81] op_sel_hi:[1,0]
	v_pk_mul_f32 v[4:5], v[4:5], v[80:81] op_sel_hi:[1,0]
	v_pk_mul_f32 v[2:3], v[2:3], v[80:81] op_sel_hi:[1,0]
	v_pk_mul_f32 v[0:1], v[0:1], v[80:81] op_sel_hi:[1,0]
	v_mov_b32_e32 v80, v111
	s_branch .LBB0_791

.Lmy_join:
	s_cmp_eq_u32 s5, 34
	s_cbranch_scc1 .Lmy_nodma
	s_bitcmp1_b32 s5, 0
	s_cselect_b32 s3, 0xa000, 0
	v_lshl_add_u64 v[180:181], v[162:163], 0, s[94:95]
	s_mov_b64 s[6:7], 0x27706000
	s_add_i32 s3, s3, 0
	v_lshl_add_u64 v[214:215], v[180:181], 0, s[6:7]
	s_add_i32 s8, s3, s94
	s_mov_b32 m0, s8
	s_mov_b64 s[6:7], 0x27708000
	global_load_lds_dwordx4 v[214:215], off
	v_lshl_add_u64 v[214:215], v[180:181], 0, s[6:7]
	s_add_i32 m0, s3, s64
	s_mov_b64 s[6:7], 0x2770a000
	global_load_lds_dwordx4 v[214:215], off
	v_lshl_add_u64 v[180:181], v[180:181], 0, s[6:7]
	s_add_i32 m0, s3, s65
	s_nop 0
	global_load_lds_dwordx4 v[180:181], off
	v_lshl_add_u64 v[180:181], v[160:161], 0, s[94:95]
	s_mov_b64 s[6:7], 0x28404000
	v_lshl_add_u64 v[214:215], v[180:181], 0, s[6:7]
	s_add_i32 m0, s8, 0x3000
	s_mov_b64 s[6:7], 0x28406000
	global_load_lds_dwordx4 v[214:215], off
	v_lshl_add_u64 v[180:181], v[180:181], 0, s[6:7]
	s_add_i32 m0, s8, 0x8000
	s_nop 0
	global_load_lds_dwordx4 v[180:181], off

.LBB0_793:
	s_nop 0
	s_nop 0
	s_nop 0
	s_nop 0
	s_nop 0
	s_nop 0
	s_nop 0
	s_nop 0
	s_nop 0
	s_nop 0
	s_nop 0
	s_nop 0
	s_nop 0
	s_nop 0
	s_nop 0
	s_and_b32 s2, s4, 0x7f
	s_lshl_b32 s3, s2, 3
	v_readlane_b32 s5, v250, 0
	s_add_i32 s3, s3, s5
	v_mov_b32_e32 v64, 0x4400
	v_mad_u64_u32 v[134:135], s[6:7], s3, v64, v[154:155]
	s_cmpk_gt_u32 s4, 0x7f
	s_mov_b64 s[8:9], -1
	s_cbranch_scc0 .LBB0_801
	v_readlane_b32 s6, v250, 15
	v_readlane_b32 s7, v250, 16
	s_andn2_b64 vcc, exec, s[6:7]
	s_cbranch_vccnz .LBB0_800
	s_lshl_b32 s2, s2, 6
	v_readlane_b32 s3, v252, 21
	s_add_u32 s8, s3, s2
	v_readlane_b32 s2, v252, 22
	s_addc_u32 s9, s2, 0
	s_mov_b32 s2, 0x100001
	s_branch .LBB0_797
